# FFN1-down GEMM epilogue: gain fragments loaded once, residual fragments prefetched three row groups ahead, counted waits
# speedup vs baseline: 1.0221x; 1.0001x over previous
.LBB0_466:
	v_lshl_add_u32 v24, s51, 8, v160
	v_lshl_or_b32 v18, s50, 8, v162
	v_ashrrev_i32_e32 v25, 31, v24
	v_ashrrev_i32_e32 v19, 31, v18
	v_lshlrev_b64 v[16:17], 11, v[24:25]
	v_lshl_add_u64 v[40:41], v[16:17], 0, v[18:19]
	v_lshl_add_u64 v[156:157], v[40:41], 2, s[48:49]
	v_readlane_b32 s52, v251, 8
	v_cndmask_b32_e64 v16, 0, 1, s[28:29]
	v_readlane_b32 s56, v251, 12
	v_readlane_b32 s57, v251, 13
	v_cmp_ne_u32_e64 s[10:11], 1, v16
	s_andn2_b64 vcc, exec, s[28:29]
	v_lshl_add_u64 v[158:159], v[40:41], 1, s[56:57]
	v_lshl_add_u64 v[16:17], v[18:19], 2, s[60:61]
	v_readlane_b32 s53, v251, 9
	v_readlane_b32 s54, v251, 10
	v_readlane_b32 s55, v251, 11
	v_readlane_b32 s58, v251, 14
	v_readlane_b32 s59, v251, 15
	v_mov_b32_e32 v246, 0x20000
	v_mov_b32_e32 v247, 0
	s_cbranch_vccnz .Lp2e_nog
	global_load_dwordx4 v[228:231], v[16:17], off
	global_load_dwordx4 v[232:235], v[16:17], off offset:16
	global_load_dwordx4 v[236:239], v[16:17], off offset:512
	global_load_dwordx4 v[240:243], v[16:17], off offset:528
.Lp2e_nog:
	v_mov_b32_e32 v244, v156
	v_mov_b32_e32 v245, v157
	global_load_dwordx4 v[176:179], v[244:245], off
	global_load_dwordx4 v[180:183], v[244:245], off offset:16
	global_load_dwordx4 v[184:187], v[244:245], off offset:512
	global_load_dwordx4 v[192:195], v[244:245], off offset:528
	v_lshl_add_u64 v[244:245], v[244:245], 0, v[246:247]
	global_load_dwordx4 v[196:199], v[244:245], off
	global_load_dwordx4 v[200:203], v[244:245], off offset:16
	global_load_dwordx4 v[204:207], v[244:245], off offset:512
	global_load_dwordx4 v[208:211], v[244:245], off offset:528
	v_lshl_add_u64 v[244:245], v[244:245], 0, v[246:247]
	global_load_dwordx4 v[212:215], v[244:245], off
	global_load_dwordx4 v[216:219], v[244:245], off offset:16
	global_load_dwordx4 v[220:223], v[244:245], off offset:512
	global_load_dwordx4 v[224:227], v[244:245], off offset:528
	v_lshl_add_u64 v[244:245], v[244:245], 0, v[246:247]
	s_waitcnt vmcnt(10)
	s_nop 1
	v_mov_b32_e32 v168, v176
	v_mov_b32_e32 v169, v177
	v_mov_b32_e32 v170, v178
	v_mov_b32_e32 v171, v179
	v_mov_b32_e32 v172, v180
	v_mov_b32_e32 v173, v181
	v_mov_b32_e32 v174, v182
	v_mov_b32_e32 v175, v183
	v_pk_add_f32 v[148:149], v[148:149], v[170:171]
	v_pk_add_f32 v[150:151], v[150:151], v[168:169]
	v_pk_add_f32 v[26:27], v[152:153], v[174:175]
	v_pk_add_f32 v[42:43], v[154:155], v[172:173]
	v_cvt_pk_bf16_f32 v152, v150, v151
	v_cvt_pk_bf16_f32 v153, v148, v149
	v_cvt_pk_bf16_f32 v154, v42, v43
	v_cvt_pk_bf16_f32 v155, v26, v27
	global_store_dwordx4 v[158:159], v[152:155], off
	s_cbranch_vccnz .LBB0_468
	v_readlane_b32 s2, v252, 9
	v_readlane_b32 s3, v252, 10
	s_nop 3
	v_mov_b32_e32 v152, v228
	v_mov_b32_e32 v153, v229
	v_mov_b32_e32 v154, v230
	v_mov_b32_e32 v155, v231
	v_mov_b32_e32 v168, v232
	v_mov_b32_e32 v169, v233
	v_mov_b32_e32 v170, v234
	v_mov_b32_e32 v171, v235
	v_pk_mul_f32 v[154:155], v[148:149], v[154:155]
	v_pk_mul_f32 v[152:153], v[150:151], v[152:153]
	v_pk_mul_f32 v[170:171], v[26:27], v[170:171]
	v_pk_mul_f32 v[168:169], v[42:43], v[168:169]
	v_cvt_pk_bf16_f32 v152, v152, v153
	v_cvt_pk_bf16_f32 v153, v154, v155
	v_cvt_pk_bf16_f32 v154, v168, v169
	v_cvt_pk_bf16_f32 v155, v170, v171
	v_lshl_add_u64 v[168:169], v[40:41], 1, s[2:3]
	global_store_dwordx4 v[168:169], v[152:155], off
.LBB0_468:
	s_nop 0
	s_and_b64 vcc, exec, s[10:11]
	s_waitcnt vmcnt(9)
	s_nop 1
	v_mov_b32_e32 v152, v184
	v_mov_b32_e32 v153, v185
	v_mov_b32_e32 v154, v186
	v_mov_b32_e32 v155, v187
	v_mov_b32_e32 v168, v192
	v_mov_b32_e32 v169, v193
	v_mov_b32_e32 v170, v194
	v_mov_b32_e32 v171, v195
	global_load_dwordx4 v[176:179], v[244:245], off
	global_load_dwordx4 v[180:183], v[244:245], off offset:16
	global_load_dwordx4 v[184:187], v[244:245], off offset:512
	global_load_dwordx4 v[192:195], v[244:245], off offset:528
	v_lshl_add_u64 v[244:245], v[244:245], 0, v[246:247]
	v_lshl_add_u64 v[244:245], v[244:245], 0, v[246:247]
	v_lshl_add_u64 v[244:245], v[244:245], 0, v[246:247]
	v_lshl_add_u64 v[244:245], v[244:245], 0, v[246:247]
	v_lshl_add_u64 v[244:245], v[244:245], 0, v[246:247]
	v_pk_add_f32 v[146:147], v[146:147], v[154:155]
	v_pk_add_f32 v[144:145], v[144:145], v[152:153]
	v_pk_add_f32 v[126:127], v[126:127], v[170:171]
	v_pk_add_f32 v[124:125], v[124:125], v[168:169]
	v_cvt_pk_bf16_f32 v152, v144, v145
	v_cvt_pk_bf16_f32 v153, v146, v147
	v_cvt_pk_bf16_f32 v154, v124, v125
	v_cvt_pk_bf16_f32 v155, v126, v127
	global_store_dwordx4 v[158:159], v[152:155], off offset:256
	s_cbranch_vccnz .LBB0_470
	v_lshlrev_b64 v[40:41], 1, v[40:41]
	v_readlane_b32 s2, v252, 9
	v_or_b32_e32 v40, 0x100, v40
	v_readlane_b32 s3, v252, 10
	s_nop 3
	v_mov_b32_e32 v152, v236
	v_mov_b32_e32 v153, v237
	v_mov_b32_e32 v154, v238
	v_mov_b32_e32 v155, v239
	v_mov_b32_e32 v156, v240
	v_mov_b32_e32 v157, v241
	v_mov_b32_e32 v158, v242
	v_mov_b32_e32 v159, v243
	v_pk_mul_f32 v[154:155], v[146:147], v[154:155]
	v_pk_mul_f32 v[152:153], v[144:145], v[152:153]
	v_pk_mul_f32 v[158:159], v[126:127], v[158:159]
	v_pk_mul_f32 v[156:157], v[124:125], v[156:157]
	v_cvt_pk_bf16_f32 v152, v152, v153
	v_cvt_pk_bf16_f32 v153, v154, v155
	v_cvt_pk_bf16_f32 v154, v156, v157
	v_cvt_pk_bf16_f32 v155, v158, v159
	v_lshl_add_u64 v[40:41], s[2:3], 0, v[40:41]
	global_store_dwordx4 v[40:41], v[152:155], off

.LBB0_472:
	s_or_b64 exec, exec, s[2:3]
	v_or_b32_e32 v26, 16, v24
	s_waitcnt lgkmcnt(0)
	v_ashrrev_i32_e32 v27, 31, v26
	v_lshlrev_b64 v[40:41], 11, v[26:27]
	v_lshl_add_u64 v[124:125], v[40:41], 0, v[18:19]
	v_lshl_add_u64 v[126:127], v[124:125], 2, s[48:49]
	v_readlane_b32 s52, v251, 8
	v_readlane_b32 s56, v251, 12
	v_readlane_b32 s57, v251, 13
	s_and_b64 vcc, exec, s[10:11]
	v_readlane_b32 s53, v251, 9
	v_lshl_add_u64 v[144:145], v[124:125], 1, s[56:57]
	v_readlane_b32 s54, v251, 10
	v_readlane_b32 s55, v251, 11
	v_readlane_b32 s58, v251, 14
	v_readlane_b32 s59, v251, 15
	s_waitcnt vmcnt(13)
	s_nop 1
	v_mov_b32_e32 v40, v196
	v_mov_b32_e32 v41, v197
	v_mov_b32_e32 v42, v198
	v_mov_b32_e32 v43, v199
	v_pk_add_f32 v[118:119], v[118:119], v[42:43]
	v_pk_add_f32 v[116:117], v[116:117], v[40:41]
	s_waitcnt vmcnt(12)
	s_nop 1
	v_mov_b32_e32 v148, v200
	v_mov_b32_e32 v149, v201
	v_mov_b32_e32 v150, v202
	v_mov_b32_e32 v151, v203
	v_pk_add_f32 v[40:41], v[120:121], v[150:151]
	v_pk_add_f32 v[42:43], v[122:123], v[148:149]
	v_cvt_pk_bf16_f32 v120, v116, v117
	v_cvt_pk_bf16_f32 v121, v118, v119
	v_cvt_pk_bf16_f32 v122, v42, v43
	v_cvt_pk_bf16_f32 v123, v40, v41
	global_store_dwordx4 v[144:145], v[120:123], off
	s_cbranch_vccnz .LBB0_474
	v_readlane_b32 s2, v252, 9
	v_readlane_b32 s3, v252, 10
	s_nop 3
	v_mov_b32_e32 v120, v228
	v_mov_b32_e32 v121, v229
	v_mov_b32_e32 v122, v230
	v_mov_b32_e32 v123, v231
	v_mov_b32_e32 v148, v232
	v_mov_b32_e32 v149, v233
	v_mov_b32_e32 v150, v234
	v_mov_b32_e32 v151, v235
	v_pk_mul_f32 v[122:123], v[118:119], v[122:123]
	v_pk_mul_f32 v[120:121], v[116:117], v[120:121]
	v_pk_mul_f32 v[150:151], v[40:41], v[150:151]
	v_pk_mul_f32 v[148:149], v[42:43], v[148:149]
	v_cvt_pk_bf16_f32 v120, v120, v121
	v_cvt_pk_bf16_f32 v121, v122, v123
	v_cvt_pk_bf16_f32 v122, v148, v149
	v_cvt_pk_bf16_f32 v123, v150, v151
	v_lshl_add_u64 v[148:149], v[124:125], 1, s[2:3]
	global_store_dwordx4 v[148:149], v[120:123], off
.LBB0_474:
	s_nop 0
	s_and_b64 vcc, exec, s[10:11]
	s_waitcnt vmcnt(12)
	s_nop 1
	v_mov_b32_e32 v120, v204
	v_mov_b32_e32 v121, v205
	v_mov_b32_e32 v122, v206
	v_mov_b32_e32 v123, v207
	v_pk_add_f32 v[114:115], v[114:115], v[122:123]
	v_pk_add_f32 v[112:113], v[112:113], v[120:121]
	s_waitcnt vmcnt(11)
	s_nop 1
	v_mov_b32_e32 v148, v208
	v_mov_b32_e32 v149, v209
	v_mov_b32_e32 v150, v210
	v_mov_b32_e32 v151, v211
	global_load_dwordx4 v[196:199], v[244:245], off
	global_load_dwordx4 v[200:203], v[244:245], off offset:16
	global_load_dwordx4 v[204:207], v[244:245], off offset:512
	global_load_dwordx4 v[208:211], v[244:245], off offset:528
	v_lshl_add_u64 v[244:245], v[244:245], 0, v[246:247]
	v_pk_add_f32 v[110:111], v[110:111], v[150:151]
	v_pk_add_f32 v[108:109], v[108:109], v[148:149]
	v_cvt_pk_bf16_f32 v120, v112, v113
	v_cvt_pk_bf16_f32 v121, v114, v115
	v_cvt_pk_bf16_f32 v122, v108, v109
	v_cvt_pk_bf16_f32 v123, v110, v111
	global_store_dwordx4 v[144:145], v[120:123], off offset:256
	s_cbranch_vccnz .LBB0_476
	v_lshlrev_b64 v[124:125], 1, v[124:125]
	v_readlane_b32 s2, v252, 9
	v_or_b32_e32 v124, 0x100, v124
	v_readlane_b32 s3, v252, 10
	s_nop 3
	v_mov_b32_e32 v120, v236
	v_mov_b32_e32 v121, v237
	v_mov_b32_e32 v122, v238
	v_mov_b32_e32 v123, v239
	v_mov_b32_e32 v148, v240
	v_mov_b32_e32 v149, v241
	v_mov_b32_e32 v150, v242
	v_mov_b32_e32 v151, v243
	v_pk_mul_f32 v[122:123], v[114:115], v[122:123]
	v_pk_mul_f32 v[120:121], v[112:113], v[120:121]
	v_pk_mul_f32 v[126:127], v[110:111], v[150:151]
	v_pk_mul_f32 v[144:145], v[108:109], v[148:149]
	v_cvt_pk_bf16_f32 v120, v120, v121
	v_cvt_pk_bf16_f32 v121, v122, v123
	v_cvt_pk_bf16_f32 v122, v144, v145
	v_cvt_pk_bf16_f32 v123, v126, v127
	v_lshl_add_u64 v[124:125], s[2:3], 0, v[124:125]
	global_store_dwordx4 v[124:125], v[120:123], off

.LBB0_478:
	s_or_b64 exec, exec, s[2:3]
	v_or_b32_e32 v26, 32, v24
	v_ashrrev_i32_e32 v27, 31, v26
	s_waitcnt lgkmcnt(0)
	v_lshlrev_b64 v[40:41], 11, v[26:27]
	v_lshl_add_u64 v[108:109], v[40:41], 0, v[18:19]
	v_lshl_add_u64 v[110:111], v[108:109], 2, s[48:49]
	v_readlane_b32 s52, v251, 8
	v_readlane_b32 s56, v251, 12
	v_readlane_b32 s57, v251, 13
	s_and_b64 vcc, exec, s[10:11]
	v_readlane_b32 s53, v251, 9
	v_lshl_add_u64 v[112:113], v[108:109], 1, s[56:57]
	v_readlane_b32 s54, v251, 10
	v_readlane_b32 s55, v251, 11
	v_readlane_b32 s58, v251, 14
	v_readlane_b32 s59, v251, 15
	s_waitcnt vmcnt(15)
	s_nop 1
	v_mov_b32_e32 v40, v212
	v_mov_b32_e32 v41, v213
	v_mov_b32_e32 v42, v214
	v_mov_b32_e32 v43, v215
	v_pk_add_f32 v[100:101], v[100:101], v[42:43]
	v_pk_add_f32 v[102:103], v[102:103], v[40:41]
	s_waitcnt vmcnt(14)
	s_nop 1
	v_mov_b32_e32 v114, v216
	v_mov_b32_e32 v115, v217
	v_mov_b32_e32 v116, v218
	v_mov_b32_e32 v117, v219
	v_pk_add_f32 v[40:41], v[104:105], v[116:117]
	v_pk_add_f32 v[42:43], v[106:107], v[114:115]
	v_cvt_pk_bf16_f32 v104, v102, v103
	v_cvt_pk_bf16_f32 v105, v100, v101
	v_cvt_pk_bf16_f32 v106, v42, v43
	v_cvt_pk_bf16_f32 v107, v40, v41
	global_store_dwordx4 v[112:113], v[104:107], off
	s_cbranch_vccnz .LBB0_480
	v_readlane_b32 s2, v252, 9
	v_readlane_b32 s3, v252, 10
	s_nop 3
	v_mov_b32_e32 v104, v228
	v_mov_b32_e32 v105, v229
	v_mov_b32_e32 v106, v230
	v_mov_b32_e32 v107, v231
	v_mov_b32_e32 v114, v232
	v_mov_b32_e32 v115, v233
	v_mov_b32_e32 v116, v234
	v_mov_b32_e32 v117, v235
	v_pk_mul_f32 v[106:107], v[100:101], v[106:107]
	v_pk_mul_f32 v[104:105], v[102:103], v[104:105]
	v_pk_mul_f32 v[116:117], v[40:41], v[116:117]
	v_pk_mul_f32 v[114:115], v[42:43], v[114:115]
	v_cvt_pk_bf16_f32 v104, v104, v105
	v_cvt_pk_bf16_f32 v105, v106, v107
	v_cvt_pk_bf16_f32 v106, v114, v115
	v_cvt_pk_bf16_f32 v107, v116, v117
	v_lshl_add_u64 v[114:115], v[108:109], 1, s[2:3]
	global_store_dwordx4 v[114:115], v[104:107], off
.LBB0_480:
	s_nop 0
	s_and_b64 vcc, exec, s[10:11]
	s_waitcnt vmcnt(14)
	s_nop 1
	v_mov_b32_e32 v104, v220
	v_mov_b32_e32 v105, v221
	v_mov_b32_e32 v106, v222
	v_mov_b32_e32 v107, v223
	v_pk_add_f32 v[98:99], v[98:99], v[106:107]
	v_pk_add_f32 v[96:97], v[96:97], v[104:105]
	s_waitcnt vmcnt(13)
	s_nop 1
	v_mov_b32_e32 v114, v224
	v_mov_b32_e32 v115, v225
	v_mov_b32_e32 v116, v226
	v_mov_b32_e32 v117, v227
	global_load_dwordx4 v[212:215], v[244:245], off
	global_load_dwordx4 v[216:219], v[244:245], off offset:16
	global_load_dwordx4 v[220:223], v[244:245], off offset:512
	global_load_dwordx4 v[224:227], v[244:245], off offset:528
	v_lshl_add_u64 v[244:245], v[244:245], 0, v[246:247]
	v_pk_add_f32 v[94:95], v[94:95], v[116:117]
	v_pk_add_f32 v[92:93], v[92:93], v[114:115]
	v_cvt_pk_bf16_f32 v104, v96, v97
	v_cvt_pk_bf16_f32 v105, v98, v99
	v_cvt_pk_bf16_f32 v106, v92, v93
	v_cvt_pk_bf16_f32 v107, v94, v95
	global_store_dwordx4 v[112:113], v[104:107], off offset:256
	s_cbranch_vccnz .LBB0_482
	v_lshlrev_b64 v[108:109], 1, v[108:109]
	v_readlane_b32 s2, v252, 9
	v_or_b32_e32 v108, 0x100, v108
	v_readlane_b32 s3, v252, 10
	s_nop 3
	v_mov_b32_e32 v104, v236
	v_mov_b32_e32 v105, v237
	v_mov_b32_e32 v106, v238
	v_mov_b32_e32 v107, v239
	v_mov_b32_e32 v110, v240
	v_mov_b32_e32 v111, v241
	v_mov_b32_e32 v112, v242
	v_mov_b32_e32 v113, v243
	v_pk_mul_f32 v[106:107], v[98:99], v[106:107]
	v_pk_mul_f32 v[104:105], v[96:97], v[104:105]
	v_pk_mul_f32 v[112:113], v[94:95], v[112:113]
	v_pk_mul_f32 v[110:111], v[92:93], v[110:111]
	v_cvt_pk_bf16_f32 v104, v104, v105
	v_cvt_pk_bf16_f32 v105, v106, v107
	v_cvt_pk_bf16_f32 v106, v110, v111
	v_cvt_pk_bf16_f32 v107, v112, v113
	v_lshl_add_u64 v[108:109], s[2:3], 0, v[108:109]
	global_store_dwordx4 v[108:109], v[104:107], off

.LBB0_484:
	s_or_b64 exec, exec, s[2:3]
	v_or_b32_e32 v26, 48, v24
	v_ashrrev_i32_e32 v27, 31, v26
	s_waitcnt lgkmcnt(0)
	v_lshlrev_b64 v[40:41], 11, v[26:27]
	v_lshl_add_u64 v[92:93], v[40:41], 0, v[18:19]
	v_lshl_add_u64 v[94:95], v[92:93], 2, s[48:49]
	v_readlane_b32 s52, v251, 8
	v_readlane_b32 s56, v251, 12
	v_readlane_b32 s57, v251, 13
	s_and_b64 vcc, exec, s[10:11]
	v_readlane_b32 s53, v251, 9
	v_lshl_add_u64 v[96:97], v[92:93], 1, s[56:57]
	v_readlane_b32 s54, v251, 10
	v_readlane_b32 s55, v251, 11
	v_readlane_b32 s58, v251, 14
	v_readlane_b32 s59, v251, 15
	s_waitcnt vmcnt(16)
	s_nop 1
	v_mov_b32_e32 v40, v176
	v_mov_b32_e32 v41, v177
	v_mov_b32_e32 v42, v178
	v_mov_b32_e32 v43, v179
	v_pk_add_f32 v[84:85], v[84:85], v[42:43]
	v_pk_add_f32 v[86:87], v[86:87], v[40:41]
	s_waitcnt vmcnt(15)
	s_nop 1
	v_mov_b32_e32 v98, v180
	v_mov_b32_e32 v99, v181
	v_mov_b32_e32 v100, v182
	v_mov_b32_e32 v101, v183
	v_pk_add_f32 v[40:41], v[88:89], v[100:101]
	v_pk_add_f32 v[42:43], v[90:91], v[98:99]
	v_cvt_pk_bf16_f32 v88, v86, v87
	v_cvt_pk_bf16_f32 v89, v84, v85
	v_cvt_pk_bf16_f32 v90, v42, v43
	v_cvt_pk_bf16_f32 v91, v40, v41
	global_store_dwordx4 v[96:97], v[88:91], off
	s_cbranch_vccnz .LBB0_486
	v_readlane_b32 s2, v252, 9
	v_readlane_b32 s3, v252, 10
	s_nop 3
	v_mov_b32_e32 v88, v228
	v_mov_b32_e32 v89, v229
	v_mov_b32_e32 v90, v230
	v_mov_b32_e32 v91, v231
	v_mov_b32_e32 v98, v232
	v_mov_b32_e32 v99, v233
	v_mov_b32_e32 v100, v234
	v_mov_b32_e32 v101, v235
	v_pk_mul_f32 v[90:91], v[84:85], v[90:91]
	v_pk_mul_f32 v[88:89], v[86:87], v[88:89]
	v_pk_mul_f32 v[100:101], v[40:41], v[100:101]
	v_pk_mul_f32 v[98:99], v[42:43], v[98:99]
	v_cvt_pk_bf16_f32 v88, v88, v89
	v_cvt_pk_bf16_f32 v89, v90, v91
	v_cvt_pk_bf16_f32 v90, v98, v99
	v_cvt_pk_bf16_f32 v91, v100, v101
	v_lshl_add_u64 v[98:99], v[92:93], 1, s[2:3]
	global_store_dwordx4 v[98:99], v[88:91], off
.LBB0_486:
	s_nop 0
	s_and_b64 vcc, exec, s[10:11]
	s_waitcnt vmcnt(15)
	s_nop 1
	v_mov_b32_e32 v88, v184
	v_mov_b32_e32 v89, v185
	v_mov_b32_e32 v90, v186
	v_mov_b32_e32 v91, v187
	v_pk_add_f32 v[82:83], v[82:83], v[90:91]
	v_pk_add_f32 v[80:81], v[80:81], v[88:89]
	s_waitcnt vmcnt(14)
	s_nop 1
	v_mov_b32_e32 v98, v192
	v_mov_b32_e32 v99, v193
	v_mov_b32_e32 v100, v194
	v_mov_b32_e32 v101, v195
	global_load_dwordx4 v[176:179], v[244:245], off
	global_load_dwordx4 v[180:183], v[244:245], off offset:16
	global_load_dwordx4 v[184:187], v[244:245], off offset:512
	global_load_dwordx4 v[192:195], v[244:245], off offset:528
	v_lshl_add_u64 v[244:245], v[244:245], 0, v[246:247]
	v_pk_add_f32 v[78:79], v[78:79], v[100:101]
	v_pk_add_f32 v[76:77], v[76:77], v[98:99]
	v_cvt_pk_bf16_f32 v88, v80, v81
	v_cvt_pk_bf16_f32 v89, v82, v83
	v_cvt_pk_bf16_f32 v90, v76, v77
	v_cvt_pk_bf16_f32 v91, v78, v79
	global_store_dwordx4 v[96:97], v[88:91], off offset:256
	s_cbranch_vccnz .LBB0_488
	v_lshlrev_b64 v[92:93], 1, v[92:93]
	v_readlane_b32 s2, v252, 9
	v_or_b32_e32 v92, 0x100, v92
	v_readlane_b32 s3, v252, 10
	s_nop 3
	v_mov_b32_e32 v88, v236
	v_mov_b32_e32 v89, v237
	v_mov_b32_e32 v90, v238
	v_mov_b32_e32 v91, v239
	v_mov_b32_e32 v94, v240
	v_mov_b32_e32 v95, v241
	v_mov_b32_e32 v96, v242
	v_mov_b32_e32 v97, v243
	v_pk_mul_f32 v[90:91], v[82:83], v[90:91]
	v_pk_mul_f32 v[88:89], v[80:81], v[88:89]
	v_pk_mul_f32 v[96:97], v[78:79], v[96:97]
	v_pk_mul_f32 v[94:95], v[76:77], v[94:95]
	v_cvt_pk_bf16_f32 v88, v88, v89
	v_cvt_pk_bf16_f32 v89, v90, v91
	v_cvt_pk_bf16_f32 v90, v94, v95
	v_cvt_pk_bf16_f32 v91, v96, v97
	v_lshl_add_u64 v[92:93], s[2:3], 0, v[92:93]
	global_store_dwordx4 v[92:93], v[88:91], off

.LBB0_490:
	s_or_b64 exec, exec, s[2:3]
	v_add_u32_e32 v26, 0x80, v24
	v_ashrrev_i32_e32 v27, 31, v26
	s_waitcnt lgkmcnt(0)
	v_lshlrev_b64 v[40:41], 11, v[26:27]
	v_lshl_add_u64 v[76:77], v[40:41], 0, v[18:19]
	v_lshl_add_u64 v[78:79], v[76:77], 2, s[48:49]
	v_readlane_b32 s52, v251, 8
	v_readlane_b32 s56, v251, 12
	v_readlane_b32 s57, v251, 13
	s_and_b64 vcc, exec, s[10:11]
	v_readlane_b32 s53, v251, 9
	v_lshl_add_u64 v[80:81], v[76:77], 1, s[56:57]
	v_readlane_b32 s54, v251, 10
	v_readlane_b32 s55, v251, 11
	v_readlane_b32 s58, v251, 14
	v_readlane_b32 s59, v251, 15
	s_waitcnt vmcnt(16)
	s_nop 1
	v_mov_b32_e32 v40, v196
	v_mov_b32_e32 v41, v197
	v_mov_b32_e32 v42, v198
	v_mov_b32_e32 v43, v199
	v_pk_add_f32 v[68:69], v[68:69], v[42:43]
	v_pk_add_f32 v[70:71], v[70:71], v[40:41]
	s_waitcnt vmcnt(15)
	s_nop 1
	v_mov_b32_e32 v82, v200
	v_mov_b32_e32 v83, v201
	v_mov_b32_e32 v84, v202
	v_mov_b32_e32 v85, v203
	v_pk_add_f32 v[40:41], v[72:73], v[84:85]
	v_pk_add_f32 v[42:43], v[74:75], v[82:83]
	v_cvt_pk_bf16_f32 v72, v70, v71
	v_cvt_pk_bf16_f32 v73, v68, v69
	v_cvt_pk_bf16_f32 v74, v42, v43
	v_cvt_pk_bf16_f32 v75, v40, v41
	global_store_dwordx4 v[80:81], v[72:75], off
	s_cbranch_vccnz .LBB0_492
	v_readlane_b32 s2, v252, 9
	v_readlane_b32 s3, v252, 10
	s_nop 3
	v_mov_b32_e32 v72, v228
	v_mov_b32_e32 v73, v229
	v_mov_b32_e32 v74, v230
	v_mov_b32_e32 v75, v231
	v_mov_b32_e32 v82, v232
	v_mov_b32_e32 v83, v233
	v_mov_b32_e32 v84, v234
	v_mov_b32_e32 v85, v235
	v_pk_mul_f32 v[74:75], v[68:69], v[74:75]
	v_pk_mul_f32 v[72:73], v[70:71], v[72:73]
	v_pk_mul_f32 v[84:85], v[40:41], v[84:85]
	v_pk_mul_f32 v[82:83], v[42:43], v[82:83]
	v_cvt_pk_bf16_f32 v72, v72, v73
	v_cvt_pk_bf16_f32 v73, v74, v75
	v_cvt_pk_bf16_f32 v74, v82, v83
	v_cvt_pk_bf16_f32 v75, v84, v85
	v_lshl_add_u64 v[82:83], v[76:77], 1, s[2:3]
	global_store_dwordx4 v[82:83], v[72:75], off
.LBB0_492:
	s_nop 0
	s_and_b64 vcc, exec, s[10:11]
	s_waitcnt vmcnt(15)
	s_nop 1
	v_mov_b32_e32 v72, v204
	v_mov_b32_e32 v73, v205
	v_mov_b32_e32 v74, v206
	v_mov_b32_e32 v75, v207
	v_pk_add_f32 v[66:67], v[66:67], v[74:75]
	v_pk_add_f32 v[64:65], v[64:65], v[72:73]
	s_waitcnt vmcnt(14)
	s_nop 1
	v_mov_b32_e32 v82, v208
	v_mov_b32_e32 v83, v209
	v_mov_b32_e32 v84, v210
	v_mov_b32_e32 v85, v211
	global_load_dwordx4 v[196:199], v[244:245], off
	global_load_dwordx4 v[200:203], v[244:245], off offset:16
	global_load_dwordx4 v[204:207], v[244:245], off offset:512
	global_load_dwordx4 v[208:211], v[244:245], off offset:528
	v_pk_add_f32 v[62:63], v[62:63], v[84:85]
	v_pk_add_f32 v[60:61], v[60:61], v[82:83]
	v_cvt_pk_bf16_f32 v72, v64, v65
	v_cvt_pk_bf16_f32 v73, v66, v67
	v_cvt_pk_bf16_f32 v74, v60, v61
	v_cvt_pk_bf16_f32 v75, v62, v63
	global_store_dwordx4 v[80:81], v[72:75], off offset:256
	s_cbranch_vccnz .LBB0_494
	v_lshlrev_b64 v[76:77], 1, v[76:77]
	v_readlane_b32 s2, v252, 9
	v_or_b32_e32 v76, 0x100, v76
	v_readlane_b32 s3, v252, 10
	s_nop 3
	v_mov_b32_e32 v72, v236
	v_mov_b32_e32 v73, v237
	v_mov_b32_e32 v74, v238
	v_mov_b32_e32 v75, v239
	v_mov_b32_e32 v78, v240
	v_mov_b32_e32 v79, v241
	v_mov_b32_e32 v80, v242
	v_mov_b32_e32 v81, v243
	v_pk_mul_f32 v[74:75], v[66:67], v[74:75]
	v_pk_mul_f32 v[72:73], v[64:65], v[72:73]
	v_pk_mul_f32 v[80:81], v[62:63], v[80:81]
	v_pk_mul_f32 v[78:79], v[60:61], v[78:79]
	v_cvt_pk_bf16_f32 v72, v72, v73
	v_cvt_pk_bf16_f32 v73, v74, v75
	v_cvt_pk_bf16_f32 v74, v78, v79
	v_cvt_pk_bf16_f32 v75, v80, v81
	v_lshl_add_u64 v[76:77], s[2:3], 0, v[76:77]
	global_store_dwordx4 v[76:77], v[72:75], off

.LBB0_496:
	s_or_b64 exec, exec, s[2:3]
	v_add_u32_e32 v26, 0x90, v24
	v_ashrrev_i32_e32 v27, 31, v26
	s_waitcnt lgkmcnt(0)
	v_lshlrev_b64 v[40:41], 11, v[26:27]
	v_lshl_add_u64 v[60:61], v[40:41], 0, v[18:19]
	v_lshl_add_u64 v[62:63], v[60:61], 2, s[48:49]
	v_readlane_b32 s52, v251, 8
	v_readlane_b32 s56, v251, 12
	v_readlane_b32 s57, v251, 13
	s_and_b64 vcc, exec, s[10:11]
	v_readlane_b32 s53, v251, 9
	v_lshl_add_u64 v[64:65], v[60:61], 1, s[56:57]
	v_readlane_b32 s54, v251, 10
	v_readlane_b32 s55, v251, 11
	v_readlane_b32 s58, v251, 14
	v_readlane_b32 s59, v251, 15
	s_waitcnt vmcnt(16)
	s_nop 1
	v_mov_b32_e32 v40, v212
	v_mov_b32_e32 v41, v213
	v_mov_b32_e32 v42, v214
	v_mov_b32_e32 v43, v215
	v_pk_add_f32 v[54:55], v[54:55], v[42:43]
	v_pk_add_f32 v[52:53], v[52:53], v[40:41]
	s_waitcnt vmcnt(15)
	s_nop 1
	v_mov_b32_e32 v66, v216
	v_mov_b32_e32 v67, v217
	v_mov_b32_e32 v68, v218
	v_mov_b32_e32 v69, v219
	v_pk_add_f32 v[40:41], v[56:57], v[68:69]
	v_pk_add_f32 v[42:43], v[58:59], v[66:67]
	v_cvt_pk_bf16_f32 v56, v52, v53
	v_cvt_pk_bf16_f32 v57, v54, v55
	v_cvt_pk_bf16_f32 v58, v42, v43
	v_cvt_pk_bf16_f32 v59, v40, v41
	global_store_dwordx4 v[64:65], v[56:59], off
	s_cbranch_vccnz .LBB0_498
	v_readlane_b32 s2, v252, 9
	v_readlane_b32 s3, v252, 10
	s_nop 3
	v_mov_b32_e32 v56, v228
	v_mov_b32_e32 v57, v229
	v_mov_b32_e32 v58, v230
	v_mov_b32_e32 v59, v231
	v_mov_b32_e32 v66, v232
	v_mov_b32_e32 v67, v233
	v_mov_b32_e32 v68, v234
	v_mov_b32_e32 v69, v235
	v_pk_mul_f32 v[58:59], v[54:55], v[58:59]
	v_pk_mul_f32 v[56:57], v[52:53], v[56:57]
	v_pk_mul_f32 v[68:69], v[40:41], v[68:69]
	v_pk_mul_f32 v[66:67], v[42:43], v[66:67]
	v_cvt_pk_bf16_f32 v56, v56, v57
	v_cvt_pk_bf16_f32 v57, v58, v59
	v_cvt_pk_bf16_f32 v58, v66, v67
	v_cvt_pk_bf16_f32 v59, v68, v69
	v_lshl_add_u64 v[66:67], v[60:61], 1, s[2:3]
	global_store_dwordx4 v[66:67], v[56:59], off
.LBB0_498:
	s_nop 0
	s_and_b64 vcc, exec, s[10:11]
	s_waitcnt vmcnt(15)
	s_nop 1
	v_mov_b32_e32 v56, v220
	v_mov_b32_e32 v57, v221
	v_mov_b32_e32 v58, v222
	v_mov_b32_e32 v59, v223
	v_pk_add_f32 v[50:51], v[50:51], v[58:59]
	v_pk_add_f32 v[48:49], v[48:49], v[56:57]
	s_waitcnt vmcnt(14)
	s_nop 1
	v_mov_b32_e32 v66, v224
	v_mov_b32_e32 v67, v225
	v_mov_b32_e32 v68, v226
	v_mov_b32_e32 v69, v227
	v_pk_add_f32 v[46:47], v[46:47], v[68:69]
	v_pk_add_f32 v[44:45], v[44:45], v[66:67]
	v_cvt_pk_bf16_f32 v56, v48, v49
	v_cvt_pk_bf16_f32 v57, v50, v51
	v_cvt_pk_bf16_f32 v58, v44, v45
	v_cvt_pk_bf16_f32 v59, v46, v47
	global_store_dwordx4 v[64:65], v[56:59], off offset:256
	s_cbranch_vccnz .LBB0_500
	v_lshlrev_b64 v[60:61], 1, v[60:61]
	v_readlane_b32 s2, v252, 9
	v_or_b32_e32 v60, 0x100, v60
	v_readlane_b32 s3, v252, 10
	s_nop 3
	v_mov_b32_e32 v56, v236
	v_mov_b32_e32 v57, v237
	v_mov_b32_e32 v58, v238
	v_mov_b32_e32 v59, v239
	v_mov_b32_e32 v62, v240
	v_mov_b32_e32 v63, v241
	v_mov_b32_e32 v64, v242
	v_mov_b32_e32 v65, v243
	v_pk_mul_f32 v[58:59], v[50:51], v[58:59]
	v_pk_mul_f32 v[56:57], v[48:49], v[56:57]
	v_pk_mul_f32 v[64:65], v[46:47], v[64:65]
	v_pk_mul_f32 v[62:63], v[44:45], v[62:63]
	v_cvt_pk_bf16_f32 v56, v56, v57
	v_cvt_pk_bf16_f32 v57, v58, v59
	v_cvt_pk_bf16_f32 v58, v62, v63
	v_cvt_pk_bf16_f32 v59, v64, v65
	v_lshl_add_u64 v[60:61], s[2:3], 0, v[60:61]
	global_store_dwordx4 v[60:61], v[56:59], off

.LBB0_502:
	s_or_b64 exec, exec, s[2:3]
	v_add_u32_e32 v26, 0xa0, v24
	v_ashrrev_i32_e32 v27, 31, v26
	s_waitcnt lgkmcnt(0)
	v_lshlrev_b64 v[40:41], 11, v[26:27]
	v_lshl_add_u64 v[40:41], v[40:41], 0, v[18:19]
	v_lshl_add_u64 v[42:43], v[40:41], 2, s[48:49]
	v_readlane_b32 s52, v251, 8
	v_readlane_b32 s56, v251, 12
	v_readlane_b32 s57, v251, 13
	s_and_b64 vcc, exec, s[10:11]
	v_readlane_b32 s53, v251, 9
	v_lshl_add_u64 v[44:45], v[40:41], 1, s[56:57]
	v_readlane_b32 s54, v251, 10
	v_readlane_b32 s55, v251, 11
	v_readlane_b32 s58, v251, 14
	v_readlane_b32 s59, v251, 15
	s_waitcnt vmcnt(12)
	s_nop 1
	v_mov_b32_e32 v46, v176
	v_mov_b32_e32 v47, v177
	v_mov_b32_e32 v48, v178
	v_mov_b32_e32 v49, v179
	v_pk_add_f32 v[36:37], v[36:37], v[48:49]
	v_pk_add_f32 v[38:39], v[38:39], v[46:47]
	s_waitcnt vmcnt(11)
	s_nop 1
	v_mov_b32_e32 v50, v180
	v_mov_b32_e32 v51, v181
	v_mov_b32_e32 v52, v182
	v_mov_b32_e32 v53, v183
	v_pk_add_f32 v[34:35], v[34:35], v[52:53]
	v_pk_add_f32 v[32:33], v[32:33], v[50:51]
	v_cvt_pk_bf16_f32 v46, v38, v39
	v_cvt_pk_bf16_f32 v47, v36, v37
	v_cvt_pk_bf16_f32 v48, v32, v33
	v_cvt_pk_bf16_f32 v49, v34, v35
	global_store_dwordx4 v[44:45], v[46:49], off
	s_cbranch_vccnz .LBB0_504
	v_readlane_b32 s2, v252, 9
	v_readlane_b32 s3, v252, 10
	s_nop 3
	v_mov_b32_e32 v46, v228
	v_mov_b32_e32 v47, v229
	v_mov_b32_e32 v48, v230
	v_mov_b32_e32 v49, v231
	v_mov_b32_e32 v50, v232
	v_mov_b32_e32 v51, v233
	v_mov_b32_e32 v52, v234
	v_mov_b32_e32 v53, v235
	v_pk_mul_f32 v[48:49], v[36:37], v[48:49]
	v_pk_mul_f32 v[46:47], v[38:39], v[46:47]
	v_pk_mul_f32 v[52:53], v[34:35], v[52:53]
	v_pk_mul_f32 v[50:51], v[32:33], v[50:51]
	v_cvt_pk_bf16_f32 v46, v46, v47
	v_cvt_pk_bf16_f32 v47, v48, v49
	v_cvt_pk_bf16_f32 v48, v50, v51
	v_cvt_pk_bf16_f32 v49, v52, v53
	v_lshl_add_u64 v[50:51], v[40:41], 1, s[2:3]
	global_store_dwordx4 v[50:51], v[46:49], off
.LBB0_504:
	s_nop 0
	s_and_b64 vcc, exec, s[10:11]
	s_waitcnt vmcnt(11)
	s_nop 1
	v_mov_b32_e32 v46, v184
	v_mov_b32_e32 v47, v185
	v_mov_b32_e32 v48, v186
	v_mov_b32_e32 v49, v187
	v_pk_add_f32 v[30:31], v[30:31], v[48:49]
	v_pk_add_f32 v[28:29], v[28:29], v[46:47]
	s_waitcnt vmcnt(10)
	s_nop 1
	v_mov_b32_e32 v50, v192
	v_mov_b32_e32 v51, v193
	v_mov_b32_e32 v52, v194
	v_mov_b32_e32 v53, v195
	v_pk_add_f32 v[22:23], v[22:23], v[52:53]
	v_pk_add_f32 v[20:21], v[20:21], v[50:51]
	v_cvt_pk_bf16_f32 v46, v28, v29
	v_cvt_pk_bf16_f32 v47, v30, v31
	v_cvt_pk_bf16_f32 v48, v20, v21
	v_cvt_pk_bf16_f32 v49, v22, v23
	global_store_dwordx4 v[44:45], v[46:49], off offset:256
	s_cbranch_vccnz .LBB0_506
	v_lshlrev_b64 v[50:51], 1, v[40:41]
	v_readlane_b32 s2, v252, 9
	v_or_b32_e32 v50, 0x100, v50
	v_readlane_b32 s3, v252, 10
	s_nop 3
	v_mov_b32_e32 v42, v236
	v_mov_b32_e32 v43, v237
	v_mov_b32_e32 v44, v238
	v_mov_b32_e32 v45, v239
	v_mov_b32_e32 v46, v240
	v_mov_b32_e32 v47, v241
	v_mov_b32_e32 v48, v242
	v_mov_b32_e32 v49, v243
	v_pk_mul_f32 v[44:45], v[30:31], v[44:45]
	v_pk_mul_f32 v[40:41], v[28:29], v[42:43]
	v_pk_mul_f32 v[48:49], v[22:23], v[48:49]
	v_pk_mul_f32 v[42:43], v[20:21], v[46:47]
	v_cvt_pk_bf16_f32 v40, v40, v41
	v_cvt_pk_bf16_f32 v41, v44, v45
	v_cvt_pk_bf16_f32 v42, v42, v43
	v_cvt_pk_bf16_f32 v43, v48, v49
	v_lshl_add_u64 v[44:45], s[2:3], 0, v[50:51]
	global_store_dwordx4 v[44:45], v[40:43], off

.LBB0_508:
	s_or_b64 exec, exec, s[2:3]
	v_add_u32_e32 v20, 0xb0, v24
	s_waitcnt lgkmcnt(0)
	v_ashrrev_i32_e32 v21, 31, v20
	v_lshlrev_b64 v[22:23], 11, v[20:21]
	v_lshl_add_u64 v[18:19], v[22:23], 0, v[18:19]
	v_lshl_add_u64 v[26:27], v[18:19], 2, s[48:49]
	v_readlane_b32 s52, v251, 8
	v_readlane_b32 s56, v251, 12
	v_readlane_b32 s57, v251, 13
	s_and_b64 vcc, exec, s[10:11]
	v_readlane_b32 s53, v251, 9
	v_lshl_add_u64 v[28:29], v[18:19], 1, s[56:57]
	v_readlane_b32 s54, v251, 10
	v_readlane_b32 s55, v251, 11
	v_readlane_b32 s58, v251, 14
	v_readlane_b32 s59, v251, 15
	s_waitcnt vmcnt(8)
	s_nop 1
	v_mov_b32_e32 v30, v196
	v_mov_b32_e32 v31, v197
	v_mov_b32_e32 v32, v198
	v_mov_b32_e32 v33, v199
	v_pk_add_f32 v[22:23], v[8:9], v[32:33]
	v_pk_add_f32 v[24:25], v[10:11], v[30:31]
	s_waitcnt vmcnt(7)
	s_nop 1
	v_mov_b32_e32 v34, v200
	v_mov_b32_e32 v35, v201
	v_mov_b32_e32 v36, v202
	v_mov_b32_e32 v37, v203
	v_pk_add_f32 v[8:9], v[12:13], v[36:37]
	v_pk_add_f32 v[10:11], v[14:15], v[34:35]
	v_cvt_pk_bf16_f32 v12, v24, v25
	v_cvt_pk_bf16_f32 v13, v22, v23
	v_cvt_pk_bf16_f32 v14, v10, v11
	v_cvt_pk_bf16_f32 v15, v8, v9
	global_store_dwordx4 v[28:29], v[12:15], off
	s_cbranch_vccnz .LBB0_510
	v_readlane_b32 s2, v252, 9
	v_readlane_b32 s3, v252, 10
	s_nop 3
	v_mov_b32_e32 v12, v228
	v_mov_b32_e32 v13, v229
	v_mov_b32_e32 v14, v230
	v_mov_b32_e32 v15, v231
	v_mov_b32_e32 v30, v232
	v_mov_b32_e32 v31, v233
	v_mov_b32_e32 v32, v234
	v_mov_b32_e32 v33, v235
	v_pk_mul_f32 v[14:15], v[22:23], v[14:15]
	v_pk_mul_f32 v[12:13], v[24:25], v[12:13]
	v_pk_mul_f32 v[32:33], v[8:9], v[32:33]
	v_pk_mul_f32 v[30:31], v[10:11], v[30:31]
	v_cvt_pk_bf16_f32 v12, v12, v13
	v_cvt_pk_bf16_f32 v13, v14, v15
	v_cvt_pk_bf16_f32 v14, v30, v31
	v_cvt_pk_bf16_f32 v15, v32, v33
	v_lshl_add_u64 v[30:31], v[18:19], 1, s[2:3]
	global_store_dwordx4 v[30:31], v[12:15], off
.LBB0_510:
	s_nop 0
	s_and_b64 vcc, exec, s[10:11]
	s_waitcnt vmcnt(7)
	s_nop 1
	v_mov_b32_e32 v12, v204
	v_mov_b32_e32 v13, v205
	v_mov_b32_e32 v14, v206
	v_mov_b32_e32 v15, v207
	v_pk_add_f32 v[6:7], v[6:7], v[14:15]
	v_pk_add_f32 v[4:5], v[4:5], v[12:13]
	s_waitcnt vmcnt(6)
	s_nop 1
	v_mov_b32_e32 v30, v208
	v_mov_b32_e32 v31, v209
	v_mov_b32_e32 v32, v210
	v_mov_b32_e32 v33, v211
	v_pk_add_f32 v[2:3], v[2:3], v[32:33]
	v_pk_add_f32 v[0:1], v[0:1], v[30:31]
	v_cvt_pk_bf16_f32 v12, v4, v5
	v_cvt_pk_bf16_f32 v13, v6, v7
	v_cvt_pk_bf16_f32 v14, v0, v1
	v_cvt_pk_bf16_f32 v15, v2, v3
	global_store_dwordx4 v[28:29], v[12:15], off offset:256
	s_cbranch_vccnz .LBB0_512
	v_lshlrev_b64 v[16:17], 1, v[18:19]
	v_readlane_b32 s2, v252, 9
	v_or_b32_e32 v16, 0x100, v16
	v_readlane_b32 s3, v252, 10
	s_nop 3
	v_mov_b32_e32 v12, v236
	v_mov_b32_e32 v13, v237
	v_mov_b32_e32 v14, v238
	v_mov_b32_e32 v15, v239
	v_mov_b32_e32 v26, v240
	v_mov_b32_e32 v27, v241
	v_mov_b32_e32 v28, v242
	v_mov_b32_e32 v29, v243
	v_pk_mul_f32 v[14:15], v[6:7], v[14:15]
	v_pk_mul_f32 v[12:13], v[4:5], v[12:13]
	v_pk_mul_f32 v[18:19], v[2:3], v[28:29]
	v_pk_mul_f32 v[26:27], v[0:1], v[26:27]
	v_cvt_pk_bf16_f32 v12, v12, v13
	v_cvt_pk_bf16_f32 v13, v14, v15
	v_cvt_pk_bf16_f32 v14, v26, v27
	v_cvt_pk_bf16_f32 v15, v18, v19
	v_lshl_add_u64 v[16:17], s[2:3], 0, v[16:17]
	global_store_dwordx4 v[16:17], v[12:15], off
